# counted vmcnt ladder: DSA K-fragment copies proceed per landed load instead of after vmcnt(0)
# baseline (speedup 1.0000x reference)
;   __device__ __forceinline__ u16* KIDX() const { return (u16*)(ws + O_KIDX); }
; DI void dsa_item(const Params& p, int l, int tile32, int b, char* smem) {
;     ...
;       bf16x8 kc[4][4];
; #pragma unroll
;       for (int t = 0; t < 4; ++t)
; #pragma unroll
;         for (int s = 0; s < 4; ++s) kc[t][s] = kn[t][s];
;       if (g + 1 < ngrp) {
; #pragma unroll
;         for (int t = 0; t < 4; ++t) {
;           const u16* krow = p.KIDX() + (tokbase + (g + 1) * 128 + t * 32 + c31) * 64 + 8 * hh;
; #pragma unroll
;           for (int s = 0; s < 4; ++s) kn[t][s] = *(const bf16x8*)(krow + 16 * s);
;         }
;       }
.LBB0_374:
	s_waitcnt vmcnt(15)
	v_mov_b64_e32 v[2:3], v[102:103]
	v_mov_b64_e32 v[4:5], v[104:105]
	s_waitcnt vmcnt(14)
	v_mov_b64_e32 v[98:99], v[106:107]
	v_mov_b64_e32 v[100:101], v[108:109]
	s_waitcnt vmcnt(13)
	v_mov_b64_e32 v[94:95], v[110:111]
	v_mov_b64_e32 v[96:97], v[112:113]
	s_waitcnt vmcnt(12)
	v_mov_b64_e32 v[90:91], v[114:115]
	v_mov_b64_e32 v[92:93], v[116:117]
	s_waitcnt vmcnt(11)
	v_mov_b64_e32 v[86:87], v[118:119]
	v_mov_b64_e32 v[88:89], v[120:121]
	s_waitcnt vmcnt(10)
	v_mov_b64_e32 v[82:83], v[122:123]
	v_mov_b64_e32 v[84:85], v[124:125]
	s_waitcnt vmcnt(9)
	v_mov_b64_e32 v[78:79], v[126:127]
	v_mov_b64_e32 v[80:81], v[128:129]
	s_waitcnt vmcnt(8)
	v_mov_b64_e32 v[74:75], v[130:131]
	v_mov_b64_e32 v[76:77], v[132:133]
	s_waitcnt vmcnt(7)
	v_mov_b64_e32 v[70:71], v[134:135]
	v_mov_b64_e32 v[72:73], v[136:137]
	s_waitcnt vmcnt(6)
	v_mov_b64_e32 v[66:67], v[138:139]
	v_mov_b64_e32 v[68:69], v[140:141]
	s_waitcnt vmcnt(5)
	v_mov_b64_e32 v[62:63], v[142:143]
	v_mov_b64_e32 v[64:65], v[144:145]
	s_waitcnt vmcnt(4)
	v_mov_b64_e32 v[58:59], v[146:147]
	v_mov_b64_e32 v[60:61], v[148:149]
	s_waitcnt vmcnt(3)
	v_mov_b64_e32 v[54:55], v[150:151]
	v_mov_b64_e32 v[56:57], v[152:153]
	s_waitcnt vmcnt(2)
	v_mov_b64_e32 v[50:51], v[154:155]
	v_mov_b64_e32 v[52:53], v[156:157]
	s_waitcnt vmcnt(1)
	v_mov_b64_e32 v[46:47], v[158:159]
	v_mov_b64_e32 v[48:49], v[160:161]
	s_waitcnt vmcnt(0)
	v_mov_b64_e32 v[42:43], v[162:163]
	v_mov_b64_e32 v[44:45], v[164:165]
